# P6 epilogue row-sum loads issued before the K-loop into spare VGPRs (on top of gMLP staging-wait fix)
# speedup vs baseline: 1.0104x; 1.0006x over previous
; DI void st8(bf16_t* p, const float (&v)[8]) { u32x4 w; w.x = cvtpk(v[0], v[1]); w.y = cvtpk(v[2], v[3]); w.z = cvtpk(v[4], v[5]); w.w = cvtpk(v[6], v[7]); *(u32x4*)p = w; }
; #define ACC8(v, ai, bj, m, s) do { const f32x4 a_ = acc[ai][bj][m][0] * (s), b_ = acc[ai][bj][m][1] * (s); v[0] = a_[0]; v[1] = a_[1]; v[2] = a_[2]; v[3] = a_[3]; v[4] = b_[0]; v[5] = b_[1]; v[6] = b_[2]; v[7] = b_[3]; } while (0)
; #define ITLOOP _Pragma("unroll") for (int it = 0; it < 8; ++it)
; #define BJLOOP _Pragma("unroll") for (int bj = 0; bj < 2; ++bj)
; #define SBE() __builtin_amdgcn_sched_barrier(0)
; template <int NS> DI void row_scales(const float* rsp, float inv, int grow0, float (&rs)[8]) {
; #pragma unroll
;     for (int it = 0; it < 8; ++it) rs[it] = rsp[grow0 + (it >> 2) * 128 + (it & 3) * 16];
;     if (NS != 0) {
; #pragma unroll
;         for (int it = 0; it < 8; ++it) rs[it] = __builtin_amdgcn_rsqf(rs[it] * inv + EPSN); }
; }
;     DI void operator()(const AccT& acc, const pg8::Unit& u, int wr, int wc, int fr_in, int fq_in) const {
;     ...
;             float rs[8]; row_scales<1>(b.ssq2, 1.0f / 1024.0f, grow0, rs);
;             ITLOOP { BJLOOP { float v[8]; ACC8(v, IT_AI, bj, IT_M, rs[it]);
; #pragma unroll
;                 for (int e = 0; e < 8; ++e) { const float t = fmaxf(v[e], 0.f); v[e] = t * t; }
;                 st8(b.hdn + IT_ROW * 4096 + tc0 + bj * 128, v); } SBE(); }
.LBB0_1344:
	s_lshl_b32 s21, s28, 8
	s_add_i32 s21, s21, s50
	v_mbcnt_lo_u32_b32 v148, -1, 0
	v_mbcnt_hi_u32_b32 v148, -1, v148
	s_nop 0
	v_and_or_b32 v144, v148, 15, s21
	v_ashrrev_i32_e32 v145, 31, v144
	v_lshl_add_u64 v[146:147], v[144:145], 2, s[6:7]
	v_lshlrev_b64 v[154:155], 13, v[144:145]
	s_lshl_b32 s21, s57, 8
	v_ashrrev_i32_e32 v146, 1, v148
	s_or_b32 s21, s21, s51
	v_and_b32_e32 v146, -8, v146
	v_add_u32_e32 v146, s21, v146
	v_ashrrev_i32_e32 v147, 31, v146
	v_lshl_add_u64 v[154:155], s[8:9], 0, v[154:155]
	v_lshlrev_b64 v[146:147], 1, v[146:147]
	v_lshl_add_u64 v[154:155], v[154:155], 0, v[146:147]
	s_waitcnt vmcnt(14)
	v_fmamk_f32 v145, v228, 0x3a800000, v159
	v_fmamk_f32 v148, v229, 0x3a800000, v159
	v_fmamk_f32 v150, v230, 0x3a800000, v159
	v_fmamk_f32 v152, v231, 0x3a800000, v159
	v_fmamk_f32 v156, v233, 0x3a800000, v159
	v_rsq_f32_e32 v160, v145
	v_fmamk_f32 v161, v234, 0x3a800000, v159
	v_fmamk_f32 v165, v235, 0x3a800000, v159
	v_fmamk_f32 v163, v238, 0x3a800000, v159
	v_pk_mul_f32 v[126:127], v[126:127], v[160:161] op_sel_hi:[1,0]
	v_pk_mul_f32 v[124:125], v[124:125], v[160:161] op_sel_hi:[1,0]
	v_pk_mul_f32 v[122:123], v[122:123], v[160:161] op_sel_hi:[1,0]
	v_pk_mul_f32 v[120:121], v[120:121], v[160:161] op_sel_hi:[1,0]
	v_pk_mul_f32 v[118:119], v[118:119], v[160:161] op_sel_hi:[1,0]
	v_pk_mul_f32 v[116:117], v[116:117], v[160:161] op_sel_hi:[1,0]
	v_pk_mul_f32 v[114:115], v[114:115], v[160:161] op_sel_hi:[1,0]
	v_pk_mul_f32 v[112:113], v[112:113], v[160:161] op_sel_hi:[1,0]
	v_max_f32_e32 v124, 0, v124
	v_max_f32_e32 v125, 0, v125
	v_max_f32_e32 v126, 0, v126
	v_max_f32_e32 v127, 0, v127
	v_max_f32_e32 v120, 0, v120
	v_max_f32_e32 v121, 0, v121
	v_max_f32_e32 v122, 0, v122
	v_max_f32_e32 v123, 0, v123
	v_max_f32_e32 v116, 0, v116
	v_max_f32_e32 v117, 0, v117
	v_max_f32_e32 v118, 0, v118
	v_max_f32_e32 v119, 0, v119
	v_max_f32_e32 v112, 0, v112
	v_max_f32_e32 v113, 0, v113
	v_max_f32_e32 v114, 0, v114
	v_max_f32_e32 v115, 0, v115
	v_pk_mul_f32 v[124:125], v[124:125], v[124:125]
	v_pk_mul_f32 v[126:127], v[126:127], v[126:127]
	v_pk_mul_f32 v[120:121], v[120:121], v[120:121]
	v_pk_mul_f32 v[122:123], v[122:123], v[122:123]
	v_rsq_f32_e32 v158, v152
	v_rsq_f32_e32 v152, v161
	v_pk_mul_f32 v[116:117], v[116:117], v[116:117]
	v_pk_mul_f32 v[118:119], v[118:119], v[118:119]
	v_pk_mul_f32 v[160:161], v[112:113], v[112:113]
	v_pk_mul_f32 v[166:167], v[114:115], v[114:115]
	v_cvt_pk_bf16_f32 v112, v124, v125
	v_cvt_pk_bf16_f32 v113, v126, v127
	v_cvt_pk_bf16_f32 v114, v120, v121
	v_cvt_pk_bf16_f32 v115, v122, v123
	v_rsq_f32_e32 v162, v148
	v_rsq_f32_e32 v164, v150
	v_rsq_f32_e32 v156, v156
	v_rsq_f32_e32 v150, v165
	v_rsq_f32_e32 v148, v163
	v_cvt_pk_bf16_f32 v116, v116, v117
	v_cvt_pk_bf16_f32 v117, v118, v119
	v_cvt_pk_bf16_f32 v118, v160, v161
	v_cvt_pk_bf16_f32 v119, v166, v167
	global_store_dwordx4 v[154:155], v[112:115], off
	global_store_dwordx4 v[154:155], v[116:119], off offset:256
	s_nop 0
	v_or_b32_e32 v112, 16, v144
	v_pk_mul_f32 v[104:105], v[104:105], v[162:163] op_sel_hi:[1,0]
	v_ashrrev_i32_e32 v113, 31, v112
	v_pk_mul_f32 v[110:111], v[110:111], v[162:163] op_sel_hi:[1,0]
	v_pk_mul_f32 v[108:109], v[108:109], v[162:163] op_sel_hi:[1,0]
	v_pk_mul_f32 v[106:107], v[106:107], v[162:163] op_sel_hi:[1,0]
	v_max_f32_e32 v104, 0, v104
	v_max_f32_e32 v105, 0, v105
	v_lshlrev_b64 v[112:113], 13, v[112:113]
	v_max_f32_e32 v108, 0, v108
	v_max_f32_e32 v109, 0, v109
	v_max_f32_e32 v110, 0, v110
	v_max_f32_e32 v111, 0, v111
	v_pk_mul_f32 v[114:115], v[104:105], v[104:105]
	v_max_f32_e32 v104, 0, v106
	v_max_f32_e32 v105, 0, v107
	v_pk_mul_f32 v[108:109], v[108:109], v[108:109]
	v_pk_mul_f32 v[110:111], v[110:111], v[110:111]
	v_pk_mul_f32 v[116:117], v[104:105], v[104:105]
	v_lshl_add_u64 v[104:105], s[8:9], 0, v[112:113]
	v_pk_mul_f32 v[96:97], v[96:97], v[162:163] op_sel_hi:[1,0]
	v_lshl_add_u64 v[112:113], v[104:105], 0, v[146:147]
	v_cvt_pk_bf16_f32 v104, v108, v109
	v_cvt_pk_bf16_f32 v105, v110, v111
	v_cvt_pk_bf16_f32 v106, v114, v115
	v_cvt_pk_bf16_f32 v107, v116, v117
	v_pk_mul_f32 v[102:103], v[102:103], v[162:163] op_sel_hi:[1,0]
	v_pk_mul_f32 v[100:101], v[100:101], v[162:163] op_sel_hi:[1,0]
	v_pk_mul_f32 v[98:99], v[98:99], v[162:163] op_sel_hi:[1,0]
	v_max_f32_e32 v96, 0, v96
	v_max_f32_e32 v97, 0, v97
	global_store_dwordx4 v[112:113], v[104:107], off
	v_max_f32_e32 v100, 0, v100
	v_max_f32_e32 v101, 0, v101
	v_max_f32_e32 v102, 0, v102
	v_max_f32_e32 v103, 0, v103
	v_pk_mul_f32 v[104:105], v[96:97], v[96:97]
	v_max_f32_e32 v96, 0, v98
	v_max_f32_e32 v97, 0, v99
	v_pk_mul_f32 v[100:101], v[100:101], v[100:101]
	v_pk_mul_f32 v[102:103], v[102:103], v[102:103]
	v_pk_mul_f32 v[106:107], v[96:97], v[96:97]
	v_cvt_pk_bf16_f32 v96, v100, v101
	v_cvt_pk_bf16_f32 v97, v102, v103
	v_cvt_pk_bf16_f32 v98, v104, v105
	v_cvt_pk_bf16_f32 v99, v106, v107
	global_store_dwordx4 v[112:113], v[96:99], off offset:256
	s_nop 1
	v_or_b32_e32 v96, 32, v144
	v_pk_mul_f32 v[88:89], v[88:89], v[164:165] op_sel_hi:[1,0]
	v_ashrrev_i32_e32 v97, 31, v96
	v_pk_mul_f32 v[94:95], v[94:95], v[164:165] op_sel_hi:[1,0]
	v_pk_mul_f32 v[92:93], v[92:93], v[164:165] op_sel_hi:[1,0]
	v_pk_mul_f32 v[90:91], v[90:91], v[164:165] op_sel_hi:[1,0]
	v_max_f32_e32 v88, 0, v88
	v_max_f32_e32 v89, 0, v89
	v_lshlrev_b64 v[96:97], 13, v[96:97]
	v_max_f32_e32 v92, 0, v92
	v_max_f32_e32 v93, 0, v93
	v_max_f32_e32 v94, 0, v94
	v_max_f32_e32 v95, 0, v95
	v_pk_mul_f32 v[98:99], v[88:89], v[88:89]
	v_max_f32_e32 v88, 0, v90
	v_max_f32_e32 v89, 0, v91
	v_pk_mul_f32 v[92:93], v[92:93], v[92:93]
	v_pk_mul_f32 v[94:95], v[94:95], v[94:95]
	v_pk_mul_f32 v[100:101], v[88:89], v[88:89]
; DI void st8(bf16_t* p, const float (&v)[8]) { u32x4 w; w.x = cvtpk(v[0], v[1]); w.y = cvtpk(v[2], v[3]); w.z = cvtpk(v[4], v[5]); w.w = cvtpk(v[6], v[7]); *(u32x4*)p = w; }
; #define ACC8(v, ai, bj, m, s) do { const f32x4 a_ = acc[ai][bj][m][0] * (s), b_ = acc[ai][bj][m][1] * (s); v[0] = a_[0]; v[1] = a_[1]; v[2] = a_[2]; v[3] = a_[3]; v[4] = b_[0]; v[5] = b_[1]; v[6] = b_[2]; v[7] = b_[3]; } while (0)
; #define ITLOOP _Pragma("unroll") for (int it = 0; it < 8; ++it)
; #define BJLOOP _Pragma("unroll") for (int bj = 0; bj < 2; ++bj)
; #define SBE() __builtin_amdgcn_sched_barrier(0)
;     DI void operator()(const AccT& acc, const pg8::Unit& u, int wr, int wc, int fr_in, int fq_in) const {
;     ...
;             ITLOOP { BJLOOP { float v[8]; ACC8(v, IT_AI, bj, IT_M, rs[it]);
; #pragma unroll
;                 for (int e = 0; e < 8; ++e) { const float t = fmaxf(v[e], 0.f); v[e] = t * t; }
;                 st8(b.hdn + IT_ROW * 4096 + tc0 + bj * 128, v); } SBE(); }
	v_lshl_add_u64 v[88:89], s[8:9], 0, v[96:97]
	v_pk_mul_f32 v[80:81], v[80:81], v[164:165] op_sel_hi:[1,0]
	v_lshl_add_u64 v[96:97], v[88:89], 0, v[146:147]
	v_cvt_pk_bf16_f32 v88, v92, v93
	v_cvt_pk_bf16_f32 v89, v94, v95
	v_cvt_pk_bf16_f32 v90, v98, v99
	v_cvt_pk_bf16_f32 v91, v100, v101
	v_pk_mul_f32 v[86:87], v[86:87], v[164:165] op_sel_hi:[1,0]
	v_pk_mul_f32 v[84:85], v[84:85], v[164:165] op_sel_hi:[1,0]
	v_pk_mul_f32 v[82:83], v[82:83], v[164:165] op_sel_hi:[1,0]
	v_max_f32_e32 v80, 0, v80
	v_max_f32_e32 v81, 0, v81
	global_store_dwordx4 v[96:97], v[88:91], off
	v_max_f32_e32 v84, 0, v84
	v_max_f32_e32 v85, 0, v85
	v_max_f32_e32 v86, 0, v86
	v_max_f32_e32 v87, 0, v87
	v_pk_mul_f32 v[88:89], v[80:81], v[80:81]
	v_max_f32_e32 v80, 0, v82
	v_max_f32_e32 v81, 0, v83
	v_pk_mul_f32 v[84:85], v[84:85], v[84:85]
	v_pk_mul_f32 v[86:87], v[86:87], v[86:87]
	v_pk_mul_f32 v[90:91], v[80:81], v[80:81]
	v_cvt_pk_bf16_f32 v80, v84, v85
	v_cvt_pk_bf16_f32 v81, v86, v87
	v_cvt_pk_bf16_f32 v82, v88, v89
	v_cvt_pk_bf16_f32 v83, v90, v91
	global_store_dwordx4 v[96:97], v[80:83], off offset:256
	s_nop 1
	v_or_b32_e32 v80, 48, v144
	v_pk_mul_f32 v[72:73], v[72:73], v[158:159] op_sel_hi:[1,0]
	v_ashrrev_i32_e32 v81, 31, v80
	v_pk_mul_f32 v[78:79], v[78:79], v[158:159] op_sel_hi:[1,0]
	v_pk_mul_f32 v[76:77], v[76:77], v[158:159] op_sel_hi:[1,0]
	v_pk_mul_f32 v[74:75], v[74:75], v[158:159] op_sel_hi:[1,0]
	v_max_f32_e32 v72, 0, v72
	v_max_f32_e32 v73, 0, v73
	v_lshlrev_b64 v[80:81], 13, v[80:81]
	v_max_f32_e32 v76, 0, v76
	v_max_f32_e32 v77, 0, v77
	v_max_f32_e32 v78, 0, v78
	v_max_f32_e32 v79, 0, v79
	v_pk_mul_f32 v[82:83], v[72:73], v[72:73]
	v_max_f32_e32 v72, 0, v74
	v_max_f32_e32 v73, 0, v75
	v_pk_mul_f32 v[76:77], v[76:77], v[76:77]
	v_pk_mul_f32 v[78:79], v[78:79], v[78:79]
	v_pk_mul_f32 v[84:85], v[72:73], v[72:73]
	v_lshl_add_u64 v[72:73], s[8:9], 0, v[80:81]
	v_pk_mul_f32 v[64:65], v[64:65], v[158:159] op_sel_hi:[1,0]
	v_lshl_add_u64 v[80:81], v[72:73], 0, v[146:147]
	v_cvt_pk_bf16_f32 v72, v76, v77
	v_cvt_pk_bf16_f32 v73, v78, v79
	v_cvt_pk_bf16_f32 v74, v82, v83
	v_cvt_pk_bf16_f32 v75, v84, v85
	v_pk_mul_f32 v[70:71], v[70:71], v[158:159] op_sel_hi:[1,0]
	v_pk_mul_f32 v[68:69], v[68:69], v[158:159] op_sel_hi:[1,0]
	v_pk_mul_f32 v[66:67], v[66:67], v[158:159] op_sel_hi:[1,0]
	v_max_f32_e32 v64, 0, v64
	v_max_f32_e32 v65, 0, v65
	global_store_dwordx4 v[80:81], v[72:75], off
	v_max_f32_e32 v68, 0, v68
	v_max_f32_e32 v69, 0, v69
	v_max_f32_e32 v70, 0, v70
	v_max_f32_e32 v71, 0, v71
	v_pk_mul_f32 v[72:73], v[64:65], v[64:65]
	v_max_f32_e32 v64, 0, v66
	v_max_f32_e32 v65, 0, v67
	v_pk_mul_f32 v[68:69], v[68:69], v[68:69]
	v_pk_mul_f32 v[70:71], v[70:71], v[70:71]
	v_pk_mul_f32 v[74:75], v[64:65], v[64:65]
	v_cvt_pk_bf16_f32 v64, v68, v69
	v_cvt_pk_bf16_f32 v65, v70, v71
	v_cvt_pk_bf16_f32 v66, v72, v73
	v_cvt_pk_bf16_f32 v67, v74, v75
	global_store_dwordx4 v[80:81], v[64:67], off offset:256
	v_pk_mul_f32 v[60:61], v[60:61], v[156:157] op_sel_hi:[1,0]
	v_pk_mul_f32 v[56:57], v[56:57], v[156:157] op_sel_hi:[1,0]
	v_pk_mul_f32 v[62:63], v[62:63], v[156:157] op_sel_hi:[1,0]
	v_pk_mul_f32 v[58:59], v[58:59], v[156:157] op_sel_hi:[1,0]
	v_max_f32_e32 v60, 0, v60
	v_max_f32_e32 v61, 0, v61
	v_max_f32_e32 v56, 0, v56
	v_max_f32_e32 v57, 0, v57
	v_pk_mul_f32 v[60:61], v[60:61], v[60:61]
	v_max_f32_e32 v62, 0, v62
	v_max_f32_e32 v63, 0, v63
	v_pk_mul_f32 v[64:65], v[56:57], v[56:57]
	v_max_f32_e32 v56, 0, v58
	v_max_f32_e32 v57, 0, v59
	v_pk_mul_f32 v[62:63], v[62:63], v[62:63]
	v_pk_mul_f32 v[66:67], v[56:57], v[56:57]
	v_cvt_pk_bf16_f32 v56, v60, v61
	v_add_co_u32_e32 v60, vcc, s56, v154
	v_pk_mul_f32 v[48:49], v[48:49], v[156:157] op_sel_hi:[1,0]
	v_cvt_pk_bf16_f32 v57, v62, v63
	v_cvt_pk_bf16_f32 v58, v64, v65
	v_cvt_pk_bf16_f32 v59, v66, v67
	v_addc_co_u32_e32 v61, vcc, 0, v155, vcc
	v_pk_mul_f32 v[54:55], v[54:55], v[156:157] op_sel_hi:[1,0]
	v_pk_mul_f32 v[52:53], v[52:53], v[156:157] op_sel_hi:[1,0]
	v_pk_mul_f32 v[50:51], v[50:51], v[156:157] op_sel_hi:[1,0]
	v_max_f32_e32 v48, 0, v48
	v_max_f32_e32 v49, 0, v49
	global_store_dwordx4 v[60:61], v[56:59], off
	v_max_f32_e32 v52, 0, v52
	v_max_f32_e32 v53, 0, v53
	v_max_f32_e32 v54, 0, v54
	v_max_f32_e32 v55, 0, v55
	v_pk_mul_f32 v[56:57], v[48:49], v[48:49]
	v_max_f32_e32 v48, 0, v50
	v_max_f32_e32 v49, 0, v51
	v_pk_mul_f32 v[52:53], v[52:53], v[52:53]
	v_pk_mul_f32 v[54:55], v[54:55], v[54:55]
	v_pk_mul_f32 v[58:59], v[48:49], v[48:49]
	v_lshl_add_u64 v[68:69], v[154:155], 0, s[18:19]
	v_cvt_pk_bf16_f32 v48, v52, v53
	v_cvt_pk_bf16_f32 v49, v54, v55
	v_cvt_pk_bf16_f32 v50, v56, v57
	v_cvt_pk_bf16_f32 v51, v58, v59
	global_store_dwordx4 v[68:69], v[48:51], off offset:256
	s_nop 1
	v_add_u32_e32 v48, 0x90, v144
	v_pk_mul_f32 v[40:41], v[40:41], v[152:153] op_sel_hi:[1,0]
	v_ashrrev_i32_e32 v49, 31, v48
	v_pk_mul_f32 v[46:47], v[46:47], v[152:153] op_sel_hi:[1,0]
	v_pk_mul_f32 v[44:45], v[44:45], v[152:153] op_sel_hi:[1,0]
	v_pk_mul_f32 v[42:43], v[42:43], v[152:153] op_sel_hi:[1,0]
	v_max_f32_e32 v40, 0, v40
	v_max_f32_e32 v41, 0, v41
	v_lshlrev_b64 v[48:49], 13, v[48:49]
	v_max_f32_e32 v44, 0, v44
	v_max_f32_e32 v45, 0, v45
; #define PG8_BAR __builtin_amdgcn_s_barrier()
; DI void st8(bf16_t* p, const float (&v)[8]) { u32x4 w; w.x = cvtpk(v[0], v[1]); w.y = cvtpk(v[2], v[3]); w.z = cvtpk(v[4], v[5]); w.w = cvtpk(v[6], v[7]); *(u32x4*)p = w; }
; #define ACC8(v, ai, bj, m, s) do { const f32x4 a_ = acc[ai][bj][m][0] * (s), b_ = acc[ai][bj][m][1] * (s); v[0] = a_[0]; v[1] = a_[1]; v[2] = a_[2]; v[3] = a_[3]; v[4] = b_[0]; v[5] = b_[1]; v[6] = b_[2]; v[7] = b_[3]; } while (0)
; #define ITLOOP _Pragma("unroll") for (int it = 0; it < 8; ++it)
; #define BJLOOP _Pragma("unroll") for (int bj = 0; bj < 2; ++bj)
; #define SBE() __builtin_amdgcn_sched_barrier(0)
;     ...
;         if constexpr (ALIGN_EPI) { if (wr == 0) PG8_BAR; }
;         if constexpr (!Epi::AFTER_DRAIN) { E(acc, cur, wr, wc, fr, fq); S.done(cur); }
;         if (!has_next) break;
; #pragma unroll
;         for (int a = 0; a < 2; ++a)
; #pragma unroll
;             for (int b = 0; b < 2; ++b)
; #pragma unroll
;                 for (int m = 0; m < 4; ++m)
; #pragma unroll
;                     for (int n = 0; n < 2; ++n) acc[a][b][m][n] = (f32x4){0.f, 0.f, 0.f, 0.f};
;         cur = nxt; cA = nA; cB = nB; ++ui;
;         if constexpr (ALIGN_EPI) { if (wr == 1) PG8_BAR; }
;     DI void operator()(const AccT& acc, const pg8::Unit& u, int wr, int wc, int fr_in, int fq_in) const {
;     ...
;             ITLOOP { BJLOOP { float v[8]; ACC8(v, IT_AI, bj, IT_M, rs[it]);
; #pragma unroll
;                 for (int e = 0; e < 8; ++e) { const float t = fmaxf(v[e], 0.f); v[e] = t * t; }
;                 st8(b.hdn + IT_ROW * 4096 + tc0 + bj * 128, v); } SBE(); }
	v_max_f32_e32 v46, 0, v46
	v_max_f32_e32 v47, 0, v47
	v_pk_mul_f32 v[50:51], v[40:41], v[40:41]
	v_max_f32_e32 v40, 0, v42
	v_max_f32_e32 v41, 0, v43
	v_pk_mul_f32 v[44:45], v[44:45], v[44:45]
	v_pk_mul_f32 v[46:47], v[46:47], v[46:47]
	v_pk_mul_f32 v[52:53], v[40:41], v[40:41]
	v_lshl_add_u64 v[40:41], s[8:9], 0, v[48:49]
	v_pk_mul_f32 v[32:33], v[32:33], v[152:153] op_sel_hi:[1,0]
	v_lshl_add_u64 v[48:49], v[40:41], 0, v[146:147]
	v_cvt_pk_bf16_f32 v40, v44, v45
	v_cvt_pk_bf16_f32 v41, v46, v47
	v_cvt_pk_bf16_f32 v42, v50, v51
	v_cvt_pk_bf16_f32 v43, v52, v53
	v_pk_mul_f32 v[38:39], v[38:39], v[152:153] op_sel_hi:[1,0]
	v_pk_mul_f32 v[36:37], v[36:37], v[152:153] op_sel_hi:[1,0]
	v_pk_mul_f32 v[34:35], v[34:35], v[152:153] op_sel_hi:[1,0]
	v_max_f32_e32 v32, 0, v32
	v_max_f32_e32 v33, 0, v33
	global_store_dwordx4 v[48:49], v[40:43], off
	v_max_f32_e32 v36, 0, v36
	v_max_f32_e32 v37, 0, v37
	v_max_f32_e32 v38, 0, v38
	v_max_f32_e32 v39, 0, v39
	v_pk_mul_f32 v[40:41], v[32:33], v[32:33]
	v_max_f32_e32 v32, 0, v34
	v_max_f32_e32 v33, 0, v35
	v_pk_mul_f32 v[36:37], v[36:37], v[36:37]
	v_pk_mul_f32 v[38:39], v[38:39], v[38:39]
	v_pk_mul_f32 v[42:43], v[32:33], v[32:33]
	v_cvt_pk_bf16_f32 v32, v36, v37
	v_cvt_pk_bf16_f32 v33, v38, v39
	v_cvt_pk_bf16_f32 v34, v40, v41
	v_cvt_pk_bf16_f32 v35, v42, v43
	global_store_dwordx4 v[48:49], v[32:35], off offset:256
	s_nop 1
	v_add_u32_e32 v32, 0xa0, v144
	v_pk_mul_f32 v[24:25], v[24:25], v[150:151] op_sel_hi:[1,0]
	v_ashrrev_i32_e32 v33, 31, v32
	v_pk_mul_f32 v[30:31], v[30:31], v[150:151] op_sel_hi:[1,0]
	v_pk_mul_f32 v[28:29], v[28:29], v[150:151] op_sel_hi:[1,0]
	v_pk_mul_f32 v[26:27], v[26:27], v[150:151] op_sel_hi:[1,0]
	v_max_f32_e32 v24, 0, v24
	v_max_f32_e32 v25, 0, v25
	v_lshlrev_b64 v[32:33], 13, v[32:33]
	v_max_f32_e32 v28, 0, v28
	v_max_f32_e32 v29, 0, v29
	v_max_f32_e32 v30, 0, v30
	v_max_f32_e32 v31, 0, v31
	v_pk_mul_f32 v[34:35], v[24:25], v[24:25]
	v_max_f32_e32 v24, 0, v26
	v_max_f32_e32 v25, 0, v27
	v_pk_mul_f32 v[28:29], v[28:29], v[28:29]
	v_pk_mul_f32 v[30:31], v[30:31], v[30:31]
	v_pk_mul_f32 v[36:37], v[24:25], v[24:25]
	v_lshl_add_u64 v[24:25], s[8:9], 0, v[32:33]
	v_pk_mul_f32 v[16:17], v[16:17], v[150:151] op_sel_hi:[1,0]
	v_lshl_add_u64 v[32:33], v[24:25], 0, v[146:147]
	v_cvt_pk_bf16_f32 v24, v28, v29
	v_cvt_pk_bf16_f32 v25, v30, v31
	v_cvt_pk_bf16_f32 v26, v34, v35
	v_cvt_pk_bf16_f32 v27, v36, v37
	v_pk_mul_f32 v[22:23], v[22:23], v[150:151] op_sel_hi:[1,0]
	v_pk_mul_f32 v[20:21], v[20:21], v[150:151] op_sel_hi:[1,0]
	v_pk_mul_f32 v[18:19], v[18:19], v[150:151] op_sel_hi:[1,0]
	v_max_f32_e32 v16, 0, v16
	v_max_f32_e32 v17, 0, v17
	global_store_dwordx4 v[32:33], v[24:27], off
	v_max_f32_e32 v20, 0, v20
	v_max_f32_e32 v21, 0, v21
	v_max_f32_e32 v22, 0, v22
	v_max_f32_e32 v23, 0, v23
	v_pk_mul_f32 v[24:25], v[16:17], v[16:17]
	v_max_f32_e32 v16, 0, v18
	v_max_f32_e32 v17, 0, v19
	v_pk_mul_f32 v[20:21], v[20:21], v[20:21]
	v_pk_mul_f32 v[22:23], v[22:23], v[22:23]
	v_pk_mul_f32 v[26:27], v[16:17], v[16:17]
	v_cvt_pk_bf16_f32 v16, v20, v21
	v_cvt_pk_bf16_f32 v17, v22, v23
	v_cvt_pk_bf16_f32 v18, v24, v25
	v_cvt_pk_bf16_f32 v19, v26, v27
	global_store_dwordx4 v[32:33], v[16:19], off offset:256
	s_nop 1
	v_add_u32_e32 v16, 0xb0, v144
	v_pk_mul_f32 v[8:9], v[8:9], v[148:149] op_sel_hi:[1,0]
	v_ashrrev_i32_e32 v17, 31, v16
	v_pk_mul_f32 v[14:15], v[14:15], v[148:149] op_sel_hi:[1,0]
	v_pk_mul_f32 v[12:13], v[12:13], v[148:149] op_sel_hi:[1,0]
	v_pk_mul_f32 v[10:11], v[10:11], v[148:149] op_sel_hi:[1,0]
	v_max_f32_e32 v8, 0, v8
	v_max_f32_e32 v9, 0, v9
	v_lshlrev_b64 v[16:17], 13, v[16:17]
	v_max_f32_e32 v12, 0, v12
	v_max_f32_e32 v13, 0, v13
	v_max_f32_e32 v14, 0, v14
	v_max_f32_e32 v15, 0, v15
	v_pk_mul_f32 v[18:19], v[8:9], v[8:9]
	v_max_f32_e32 v8, 0, v10
	v_max_f32_e32 v9, 0, v11
	v_pk_mul_f32 v[12:13], v[12:13], v[12:13]
	v_pk_mul_f32 v[14:15], v[14:15], v[14:15]
	v_pk_mul_f32 v[20:21], v[8:9], v[8:9]
	v_lshl_add_u64 v[8:9], s[8:9], 0, v[16:17]
	v_pk_mul_f32 v[0:1], v[0:1], v[148:149] op_sel_hi:[1,0]
	v_lshl_add_u64 v[16:17], v[8:9], 0, v[146:147]
	v_cvt_pk_bf16_f32 v8, v12, v13
	v_cvt_pk_bf16_f32 v9, v14, v15
	v_cvt_pk_bf16_f32 v10, v18, v19
	v_cvt_pk_bf16_f32 v11, v20, v21
	v_pk_mul_f32 v[6:7], v[6:7], v[148:149] op_sel_hi:[1,0]
	v_pk_mul_f32 v[4:5], v[4:5], v[148:149] op_sel_hi:[1,0]
	v_pk_mul_f32 v[2:3], v[2:3], v[148:149] op_sel_hi:[1,0]
	v_max_f32_e32 v0, 0, v0
	v_max_f32_e32 v1, 0, v1
	global_store_dwordx4 v[16:17], v[8:11], off
	v_max_f32_e32 v4, 0, v4
	v_max_f32_e32 v5, 0, v5
	v_max_f32_e32 v6, 0, v6
	v_max_f32_e32 v7, 0, v7
	v_pk_mul_f32 v[8:9], v[0:1], v[0:1]
	v_max_f32_e32 v0, 0, v2
	v_max_f32_e32 v1, 0, v3
	v_pk_mul_f32 v[4:5], v[4:5], v[4:5]
	v_pk_mul_f32 v[6:7], v[6:7], v[6:7]
	v_pk_mul_f32 v[10:11], v[0:1], v[0:1]
	v_cvt_pk_bf16_f32 v0, v4, v5
	v_cvt_pk_bf16_f32 v1, v6, v7
	v_cvt_pk_bf16_f32 v2, v8, v9
	v_cvt_pk_bf16_f32 v3, v10, v11
	global_store_dwordx4 v[16:17], v[0:3], off offset:256
	s_andn2_b64 vcc, exec, s[0:1]
	s_mov_b64 s[0:1], -1
	s_cbranch_vccnz .LBB0_1333
	s_andn2_b64 vcc, exec, s[4:5]
	s_cbranch_vccnz .LBB0_1332
	s_barrier
	s_branch .LBB0_1332
